# LN2 -> layer-3 G1 (ph16->17) team sync (H stores write-through) replaces one more grid barrier
# speedup vs baseline: 1.0541x; 1.0092x over previous
.LBB0_1921:
	s_or_b64 exec, exec, s[4:5]
	v_add_u32_e32 v3, 0xfffff000, v10
	v_lshrrev_b32_e32 v3, 11, v3
	v_mad_u32_u24 v3, v3, s28, v11
	v_cmp_lt_i32_e64 s[4:5], s29, v10
	v_mov_b32_e32 v49, v13
	v_lshl_add_u64 v[88:89], v[44:45], 0, v[34:35]
	v_cndmask_b32_e64 v12, v112, v3, s[4:5]
	v_add_u32_e32 v3, 0xfffff000, v2
	v_lshl_add_u64 v[4:5], v[12:13], 2, s[8:9]
	v_lshrrev_b32_e32 v3, 11, v3
	v_mad_u32_u24 v3, v3, s28, v11
	v_cmp_lt_i32_e64 s[4:5], s29, v2
	v_lshl_add_u64 v[86:87], v[4:5], 0, s[26:27]
	v_lshl_add_u64 v[90:91], v[4:5], 0, v[48:49]
	v_cndmask_b32_e64 v12, v112, v3, s[4:5]
	v_lshl_add_u64 v[2:3], v[86:87], 0, v[48:49]
	global_load_dwordx4 v[114:117], v[2:3], off
	global_load_dwordx4 v[118:121], v[90:91], off
	v_lshl_add_u64 v[6:7], v[12:13], 2, s[8:9]
	v_lshl_add_u64 v[94:95], v[6:7], 0, s[26:27]
	v_lshl_add_u64 v[2:3], v[94:95], 0, v[48:49]
	v_lshl_add_u64 v[92:93], v[6:7], 0, v[48:49]
	global_load_dwordx4 v[2:5], v[2:3], off
	s_waitcnt vmcnt(2)
	v_pk_add_f32 v[114:115], v[114:115], 1.0 op_sel_hi:[1,0]
	global_load_dwordx4 v[6:9], v[92:93], off
	v_pk_add_f32 v[116:117], v[116:117], 1.0 op_sel_hi:[1,0]
	s_waitcnt vmcnt(2)
	v_pk_fma_f32 v[84:85], v[84:85], v[114:115], v[118:119]
	v_pk_fma_f32 v[104:105], v[104:105], v[116:117], v[120:121]
	v_cvt_pk_bf16_f32 v84, v84, v85
	v_cvt_pk_bf16_f32 v85, v104, v105
	global_store_dwordx2 v[88:89], v[84:85], off sc1
	v_lshl_add_u64 v[84:85], v[42:43], 0, v[34:35]
	s_and_saveexec_b64 s[4:5], vcc
	s_cbranch_execz .LBB0_1923
	s_waitcnt vmcnt(2)
	v_pk_add_f32 v[4:5], v[4:5], 1.0 op_sel_hi:[1,0]
	v_pk_add_f32 v[2:3], v[2:3], 1.0 op_sel_hi:[1,0]
	s_waitcnt vmcnt(1)
	v_pk_fma_f32 v[4:5], v[102:103], v[4:5], v[8:9]
	v_pk_fma_f32 v[2:3], v[100:101], v[2:3], v[6:7]
	v_cvt_pk_bf16_f32 v5, v4, v5
	v_cvt_pk_bf16_f32 v4, v2, v3
	global_store_dwordx2 v[84:85], v[4:5], off sc1

.LBB0_1925:
	s_or_b64 exec, exec, s[4:5]
	v_mov_b32_e32 v51, v13
	v_lshl_add_u64 v[2:3], v[86:87], 0, v[50:51]
	global_load_dwordx4 v[100:103], v[2:3], off
	global_load_dwordx4 v[114:117], v[90:91], off offset:1024
	v_lshl_add_u64 v[104:105], v[94:95], 0, v[50:51]
	global_load_dwordx4 v[6:9], v[104:105], off
	global_load_dwordx4 v[2:5], v[92:93], off offset:1024
	s_waitcnt vmcnt(3)
	v_pk_add_f32 v[100:101], v[100:101], 1.0 op_sel_hi:[1,0]
	v_pk_add_f32 v[102:103], v[102:103], 1.0 op_sel_hi:[1,0]
	s_waitcnt vmcnt(2)
	v_pk_fma_f32 v[96:97], v[96:97], v[100:101], v[114:115]
	v_pk_fma_f32 v[98:99], v[98:99], v[102:103], v[116:117]
	v_cvt_pk_bf16_f32 v96, v96, v97
	v_cvt_pk_bf16_f32 v97, v98, v99
	global_store_dwordx2 v[88:89], v[96:97], off offset:512 sc1
	s_and_saveexec_b64 s[4:5], vcc
	s_cbranch_execz .LBB0_1927
	s_waitcnt vmcnt(2)
	v_pk_add_f32 v[8:9], v[8:9], 1.0 op_sel_hi:[1,0]
	v_pk_add_f32 v[6:7], v[6:7], 1.0 op_sel_hi:[1,0]
	s_waitcnt vmcnt(1)
	v_pk_fma_f32 v[4:5], v[72:73], v[8:9], v[4:5]
	v_pk_fma_f32 v[2:3], v[70:71], v[6:7], v[2:3]
	v_cvt_pk_bf16_f32 v5, v4, v5
	v_cvt_pk_bf16_f32 v4, v2, v3
	global_store_dwordx2 v[84:85], v[4:5], off offset:512 sc1

.LBB0_1929:
	s_or_b64 exec, exec, s[4:5]
	v_mov_b32_e32 v53, v13
	v_lshl_add_u64 v[2:3], v[86:87], 0, v[52:53]
	global_load_dwordx4 v[80:83], v[2:3], off
	global_load_dwordx4 v[96:99], v[90:91], off offset:2048
	v_lshl_add_u64 v[100:101], v[94:95], 0, v[52:53]
	global_load_dwordx4 v[6:9], v[100:101], off
	global_load_dwordx4 v[2:5], v[92:93], off offset:2048
	s_waitcnt vmcnt(3)
	v_pk_add_f32 v[80:81], v[80:81], 1.0 op_sel_hi:[1,0]
	v_pk_add_f32 v[82:83], v[82:83], 1.0 op_sel_hi:[1,0]
	s_waitcnt vmcnt(2)
	v_pk_fma_f32 v[70:71], v[70:71], v[80:81], v[96:97]
	v_pk_fma_f32 v[72:73], v[72:73], v[82:83], v[98:99]
	v_cvt_pk_bf16_f32 v70, v70, v71
	v_cvt_pk_bf16_f32 v71, v72, v73
	global_store_dwordx2 v[88:89], v[70:71], off offset:1024 sc1
	s_and_saveexec_b64 s[4:5], vcc
	s_cbranch_execz .LBB0_1931
	s_waitcnt vmcnt(2)
	v_pk_add_f32 v[8:9], v[8:9], 1.0 op_sel_hi:[1,0]
	v_pk_add_f32 v[6:7], v[6:7], 1.0 op_sel_hi:[1,0]
	s_waitcnt vmcnt(1)
	v_pk_fma_f32 v[4:5], v[68:69], v[8:9], v[4:5]
	v_pk_fma_f32 v[2:3], v[66:67], v[6:7], v[2:3]
	v_cvt_pk_bf16_f32 v5, v4, v5
	v_cvt_pk_bf16_f32 v4, v2, v3
	global_store_dwordx2 v[84:85], v[4:5], off offset:1024 sc1

.LBB0_1933:
	s_or_b64 exec, exec, s[4:5]
	v_mov_b32_e32 v55, v13
	v_lshl_add_u64 v[2:3], v[86:87], 0, v[54:55]
	global_load_dwordx4 v[66:69], v[2:3], off
	global_load_dwordx4 v[70:73], v[90:91], off offset:3072
	v_lshl_add_u64 v[56:57], v[94:95], 0, v[54:55]
	global_load_dwordx4 v[6:9], v[56:57], off
	global_load_dwordx4 v[2:5], v[92:93], off offset:3072
	s_waitcnt vmcnt(3)
	v_pk_add_f32 v[56:57], v[66:67], 1.0 op_sel_hi:[1,0]
	v_pk_add_f32 v[66:67], v[68:69], 1.0 op_sel_hi:[1,0]
	s_waitcnt vmcnt(2)
	v_pk_fma_f32 v[56:57], v[62:63], v[56:57], v[70:71]
	v_pk_fma_f32 v[62:63], v[64:65], v[66:67], v[72:73]
	v_cvt_pk_bf16_f32 v56, v56, v57
	v_cvt_pk_bf16_f32 v57, v62, v63
	global_store_dwordx2 v[88:89], v[56:57], off offset:1536 sc1
	s_and_saveexec_b64 s[4:5], vcc
	s_cbranch_execz .LBB0_1918
	s_waitcnt vmcnt(2)
	v_pk_add_f32 v[8:9], v[8:9], 1.0 op_sel_hi:[1,0]
	v_pk_add_f32 v[6:7], v[6:7], 1.0 op_sel_hi:[1,0]
	s_waitcnt vmcnt(1)
	v_pk_fma_f32 v[4:5], v[60:61], v[8:9], v[4:5]
	v_pk_fma_f32 v[2:3], v[58:59], v[6:7], v[2:3]
	v_cvt_pk_bf16_f32 v5, v4, v5
	v_cvt_pk_bf16_f32 v4, v2, v3
	global_store_dwordx2 v[84:85], v[4:5], off offset:1536 sc1
	s_branch .LBB0_1918
.LBB0_1935:
	s_or_b64 exec, exec, s[12:13]
	s_load_dword s66, s[0:1], 0x468
	s_waitcnt lgkmcnt(0)
	s_cmpk_lg_u32 s66, 0x200
	s_cbranch_scc1 FUSE16_ORIG
	s_cmp_lt_i32 s23, 18
	s_cbranch_scc1 FUSE16_ORIG
	s_waitcnt vmcnt(0)
	s_barrier
	v_bfe_u32 v5, v0, 6, 2
	s_and_b32 s73, s2, 0x1ff
	s_nop 1
	v_readfirstlane_b32 s67, v5
	s_cmp_lg_u32 s67, 0
	s_cbranch_scc1 FUSE16_WAIT
	s_and_b32 s67, s73, 63
	s_lshl_b32 s68, s67, 6
	s_and_b32 s69, s67, 32
	s_lshl_b32 s69, s69, 6
	s_add_u32 s68, s68, s69
	s_add_u32 s68, s68, 0x1c00
	v_mov_b32_e32 v2, s68
	v_mov_b32_e32 v3, 1
	s_mov_b64 s[70:71], exec
	s_mov_b64 exec, 1
	s_mov_b32 s74, 0
	global_atomic_add v2, v3, s[20:21]
FUSE16_SPIN:
	global_load_dword v4, v2, s[20:21] sc1
	s_waitcnt vmcnt(0)
	v_readfirstlane_b32 s69, v4
	s_cmp_ge_u32 s69, 40
	s_cbranch_scc1 FUSE16_GOT
	s_add_i32 s74, s74, 1
	s_cmp_gt_u32 s74, 0x20000
	s_cbranch_scc1 FUSE16_GOT
	s_sleep 1
	s_branch FUSE16_SPIN
FUSE16_GOT:
	s_mov_b64 exec, s[70:71]
FUSE16_WAIT:
	s_barrier
	s_branch .LBB0_1988
FUSE16_ORIG:
	s_cmp_lt_i32 s23, 18
	s_cbranch_scc1 .LBB0_1988
	s_waitcnt vmcnt(0)
	v_cmp_eq_u32_e32 vcc, 0, v47
	s_waitcnt vmcnt(0)
	v_mov_b32_e32 v2, v146
	v_mov_b32_e32 v4, v148
	s_waitcnt lgkmcnt(0)
	s_barrier
	s_and_saveexec_b64 s[4:5], vcc
	s_cbranch_execz .LBB0_1985
	v_cmp_eq_u32_e32 vcc, 0, v148
	v_mov_b32_e32 v2, v146
	v_mov_b32_e32 v4, v148
	s_waitcnt vmcnt(0) expcnt(0) lgkmcnt(0)
	s_and_saveexec_b64 s[8:9], vcc
	s_cbranch_execz .LBB0_1952
	s_load_dwordx2 s[12:13], s[6:7], 0x4
	s_add_u32 s6, s20, 0x1000
	s_addc_u32 s7, s21, 0
	s_add_u32 s10, s20, 0x1100
	s_addc_u32 s11, s21, 0
	s_waitcnt lgkmcnt(0)
	s_mul_i32 s3, s12, s3
	s_add_u32 s12, s20, 0x1200
	s_mul_i32 s3, s3, s13
	s_addc_u32 s13, s21, 0
	s_add_u32 s14, s20, 0x1300
	s_addc_u32 s15, s21, 0
	s_mov_b32 s26, 1
	v_mov_b32_e32 v18, 0
	s_branch .LBB0_1940

FUSE18_SPIN:
	global_load_dword v4, v2, s[20:21] sc1
	s_waitcnt vmcnt(0)
	v_readfirstlane_b32 s69, v4
	s_cmp_ge_u32 s69, 48
	s_cbranch_scc1 FUSE18_GOT
	s_add_i32 s74, s74, 1
	s_cmp_gt_u32 s74, 0x20000
	s_cbranch_scc1 FUSE18_GOT
	s_sleep 1
	s_branch FUSE18_SPIN

FUSE20_SPIN:
	global_load_dword v4, v2, s[20:21] sc1
	s_waitcnt vmcnt(0)
	v_readfirstlane_b32 s69, v4
	s_cmp_ge_u32 s69, 56
	s_cbranch_scc1 FUSE20_GOT
	s_add_i32 s74, s74, 1
	s_cmp_gt_u32 s74, 0x20000
	s_cbranch_scc1 FUSE20_GOT
	s_sleep 1
	s_branch FUSE20_SPIN
